# final-phase: 4 rows per wave loaded up front, counted vmcnt, interleaved reductions
# baseline (speedup 1.0000x reference)
.LBB0_20:
	s_mov_b64 s[30:31], s[78:79]
	v_writelane_b32 v209, s76, 22
	s_mov_b32 s2, s18
	s_load_dwordx4 s[16:19], s[30:31], 0xa8
	v_writelane_b32 v209, s77, 23
	v_writelane_b32 v209, s26, 24
	s_waitcnt lgkmcnt(0)
	s_mov_b64 s[4:5], -1
	v_readlane_b32 s9, v252, 12
	v_writelane_b32 v209, s27, 25
	s_waitcnt lgkmcnt(0)
	s_add_u32 s14, s18, 0x100000
	v_readlane_b32 s0, v209, 26
	v_readlane_b32 s1, v209, 27
	s_addc_u32 s15, s19, 0
	v_writelane_b32 v209, s0, 28
	s_nop 1
	v_writelane_b32 v209, s1, 29
	s_add_u32 s0, s18, 0x14e00000
	s_addc_u32 s1, s19, 0
	v_writelane_b32 v209, s0, 30
	s_nop 1
	v_writelane_b32 v209, s1, 31
	s_add_u32 s0, s18, 0x2400000
	s_addc_u32 s1, s19, 0
	v_writelane_b32 v209, s0, 32
	s_nop 1
	v_writelane_b32 v209, s1, 33
	s_add_u32 s0, s18, 0x3400000
	s_addc_u32 s1, s19, 0
	v_writelane_b32 v209, s0, 34
	s_nop 1
	v_writelane_b32 v209, s1, 35
	s_add_u32 s0, s18, 0x14400000
	s_addc_u32 s1, s19, 0
	v_writelane_b32 v209, s0, 36
	s_nop 1
	v_writelane_b32 v209, s1, 37
	s_add_u32 s0, s18, 0xe400000
	s_addc_u32 s1, s19, 0
	v_writelane_b32 v209, s0, 38
	s_nop 1
	v_writelane_b32 v209, s1, 39
	s_add_u32 s0, s18, 0x400000
	s_addc_u32 s1, s19, 0
	v_writelane_b32 v209, s0, 40
	s_cmp_lt_i32 s2, 21
	s_nop 0
	v_writelane_b32 v209, s1, 41
	v_writelane_b32 v209, s2, 42
	s_mov_b64 s[0:1], 0
	v_readlane_b32 s26, v209, 8
	s_mov_b64 s[2:3], 0
	v_readlane_b32 s20, v209, 12
	v_readlane_b32 s27, v209, 9
	v_readlane_b32 s21, v209, 13
	s_cbranch_scc1 .LBB0_29
	v_readlane_b32 s2, v209, 42
	s_cmp_eq_u32 s2, 21
	s_mov_b64 s[2:3], -1
	s_cbranch_scc0 .LBB0_28
	v_mov_b32_e32 v0, v234
	v_readlane_b32 s2, v254, 26
	v_ashrrev_i32_e32 v32, 6, v0
	v_readlane_b32 s3, v254, 27
	v_add_u32_e32 v1, s2, v32
	s_movk_i32 s2, 0x2000
	v_cmp_gt_i32_e32 vcc, s2, v1
	s_and_saveexec_b64 s[2:3], vcc
	s_cbranch_execz .LBB0_27
	s_load_dwordx2 s[4:5], s[30:31], 0xa0
	v_and_b32_e32 v36, 63, v0
	v_lshlrev_b32_e32 v37, 5, v36
	v_or_b32_e32 v20, 0x1000, v37
	v_or_b32_e32 v28, 0x1800, v37
	s_waitcnt lgkmcnt(0)
	global_load_dwordx4 v[0:3], v37, s[4:5] offset:16
	global_load_dwordx4 v[4:7], v37, s[4:5]
	global_load_dwordx4 v[8:11], v37, s[4:5] offset:2064
	global_load_dwordx4 v[12:15], v37, s[4:5] offset:2048
	global_load_dwordx4 v[16:19], v20, s[4:5] offset:16
	s_nop 0
	global_load_dwordx4 v[20:23], v20, s[4:5]
	s_nop 0
	global_load_dwordx4 v[24:27], v28, s[4:5] offset:16
	s_nop 0
	global_load_dwordx4 v[28:31], v28, s[4:5]
	v_cmp_lt_i32_e64 s[4:5], v239, v238
	v_lshlrev_b32_e32 v204, 2, v36
	v_cmp_gt_u32_e32 vcc, 32, v36
	v_cndmask_b32_e64 v33, v237, v239, s[4:5]
	v_cmp_lt_i32_e64 s[4:5], v240, v238
	v_lshlrev_b32_e32 v55, 2, v33
	s_mov_b32 s8, 1
	v_cndmask_b32_e64 v33, v237, v240, s[4:5]
	v_cmp_lt_i32_e64 s[4:5], v241, v238
	v_lshlrev_b32_e32 v56, 2, v33
	s_mov_b64 s[6:7], 0
	v_cndmask_b32_e64 v33, v237, v241, s[4:5]
	v_cmp_lt_i32_e64 s[4:5], v208, v238
	v_lshlrev_b32_e32 v57, 2, v33
	s_nop 0
	v_cndmask_b32_e64 v33, v237, v208, s[4:5]
	v_cmp_lt_i32_e64 s[4:5], v243, v238
	v_lshlrev_b32_e32 v58, 2, v33
	s_nop 0
	v_cndmask_b32_e64 v33, v237, v243, s[4:5]
	v_cmp_lt_i32_e64 s[4:5], v244, v238
	v_lshlrev_b32_e32 v59, 2, v33
	s_nop 0
	v_cndmask_b32_e64 v33, v237, v244, s[4:5]
	v_readlane_b32 s4, v254, 28
	v_lshlrev_b32_e32 v60, 2, v33
	v_ashrrev_i32_e32 v33, 31, v32
	v_add_u32_e32 v61, s4, v32
	v_readlane_b32 s4, v254, 26
	v_readlane_b32 s5, v254, 27
	s_nop 1
	v_lshl_add_u64 v[32:33], s[4:5], 0, v[32:33]
	v_lshlrev_b64 v[34:35], 7, v[32:33]
	v_lshl_add_u64 v[34:35], v[34:35], 0, v[204:205]
	v_lshl_add_u64 v[48:49], s[14:15], 0, v[34:35]
	v_lshlrev_b64 v[34:35], 12, v[32:33]
	v_lshl_or_b32 v34, v36, 4, v34
	v_lshlrev_b64 v[32:33], 13, v[32:33]
	v_lshl_add_u64 v[34:35], s[18:19], 0, v[34:35]
	s_mov_b64 s[4:5], 0x15e00800
	v_or_b32_e32 v32, v32, v37
	v_lshl_add_u64 v[50:51], v[34:35], 0, s[4:5]
	v_lshl_add_u64 v[32:33], s[16:17], 0, v[32:33]
	s_mov_b64 s[4:5], 0x1000
	v_lshl_add_u64 v[52:53], v[32:33], 0, s[4:5]
	v_readfirstlane_b32 s4, v61
	s_cmp_lt_u32 s9, 4
	s_cbranch_scc1 .Lfin_slow
	s_lshl_b32 s5, s20, 1
	s_add_i32 s5, s5, s4
	s_cmpk_gt_i32 s5, 0x1fff
	s_cbranch_scc1 .Lfin_slow
	s_cmp_eq_u32 s9, 4
	s_cbranch_scc1 .Lfin_fast
	s_add_i32 s5, s5, s20
	s_cmpk_gt_i32 s5, 0x1fff
	s_cbranch_scc1 .Lfin_fast

.Lfin_fast:
	v_readlane_b32 s10, v209, 10
	v_readlane_b32 s11, v209, 11
	v_mov_b32_e32 v54, 0
	v_mov_b32_e32 v132, 0
	v_mov_b32_e32 v134, 0
	v_mov_b32_e32 v136, 0
	v_lshl_add_u64 v[146:147], v[48:49], 0, s[26:27]
	v_lshl_add_u64 v[148:149], v[146:147], 0, s[26:27]
	v_lshl_add_u64 v[150:151], v[148:149], 0, s[26:27]
	v_lshl_add_u64 v[140:141], v[50:51], 0, s[10:11]
	v_lshl_add_u64 v[142:143], v[140:141], 0, s[10:11]
	v_lshl_add_u64 v[144:145], v[142:143], 0, s[10:11]
	s_and_saveexec_b64 s[4:5], vcc
	global_load_dword v54, v[48:49], off
	global_load_dword v132, v[146:147], off
	global_load_dword v134, v[148:149], off
	global_load_dword v136, v[150:151], off
	s_or_b64 exec, exec, s[4:5]
	global_load_dwordx4 v[64:67], v[50:51], off offset:-2048
	global_load_dwordx4 v[68:71], v[50:51], off offset:-1024
	global_load_dwordx4 v[72:75], v[50:51], off
	global_load_dwordx4 v[76:79], v[50:51], off offset:1024
	global_load_dwordx4 v[80:83], v[140:141], off offset:-2048
	global_load_dwordx4 v[84:87], v[140:141], off offset:-1024
	global_load_dwordx4 v[88:91], v[140:141], off
	global_load_dwordx4 v[92:95], v[140:141], off offset:1024
	global_load_dwordx4 v[96:99], v[142:143], off offset:-2048
	global_load_dwordx4 v[100:103], v[142:143], off offset:-1024
	global_load_dwordx4 v[104:107], v[142:143], off
	global_load_dwordx4 v[108:111], v[142:143], off offset:1024
	global_load_dwordx4 v[112:115], v[144:145], off offset:-2048
	global_load_dwordx4 v[116:119], v[144:145], off offset:-1024
	global_load_dwordx4 v[120:123], v[144:145], off
	global_load_dwordx4 v[124:127], v[144:145], off offset:1024
	v_readlane_b32 s10, v209, 14
	v_readlane_b32 s11, v209, 15
	s_mov_b32 s8, 0x800000
	s_nop 1
	v_lshl_add_u64 v[152:153], v[52:53], 0, s[10:11]
	v_lshl_add_u64 v[154:155], v[152:153], 0, s[10:11]
	v_lshl_add_u64 v[156:157], v[154:155], 0, s[10:11]
	s_waitcnt vmcnt(16)
	ds_bpermute_b32 v160, v55, v54
	ds_bpermute_b32 v161, v55, v132
	ds_bpermute_b32 v162, v55, v134
	ds_bpermute_b32 v163, v55, v136
	s_waitcnt lgkmcnt(0)
	v_add_f32_e32 v54, v54, v160
	v_add_f32_e32 v132, v132, v161
	v_add_f32_e32 v134, v134, v162
	v_add_f32_e32 v136, v136, v163
	ds_bpermute_b32 v160, v56, v54
	ds_bpermute_b32 v161, v56, v132
	ds_bpermute_b32 v162, v56, v134
	ds_bpermute_b32 v163, v56, v136
	s_waitcnt lgkmcnt(0)
	v_add_f32_e32 v54, v54, v160
	v_add_f32_e32 v132, v132, v161
	v_add_f32_e32 v134, v134, v162
	v_add_f32_e32 v136, v136, v163
	ds_bpermute_b32 v160, v57, v54
	ds_bpermute_b32 v161, v57, v132
	ds_bpermute_b32 v162, v57, v134
	ds_bpermute_b32 v163, v57, v136
	s_waitcnt lgkmcnt(0)
	v_add_f32_e32 v54, v54, v160
	v_add_f32_e32 v132, v132, v161
	v_add_f32_e32 v134, v134, v162
	v_add_f32_e32 v136, v136, v163
	ds_bpermute_b32 v160, v58, v54
	ds_bpermute_b32 v161, v58, v132
	ds_bpermute_b32 v162, v58, v134
	ds_bpermute_b32 v163, v58, v136
	s_waitcnt lgkmcnt(0)
	v_add_f32_e32 v54, v54, v160
	v_add_f32_e32 v132, v132, v161
	v_add_f32_e32 v134, v134, v162
	v_add_f32_e32 v136, v136, v163
	ds_bpermute_b32 v160, v59, v54
	ds_bpermute_b32 v161, v59, v132
	ds_bpermute_b32 v162, v59, v134
	ds_bpermute_b32 v163, v59, v136
	s_waitcnt lgkmcnt(0)
	v_add_f32_e32 v54, v54, v160
	v_add_f32_e32 v132, v132, v161
	v_add_f32_e32 v134, v134, v162
	v_add_f32_e32 v136, v136, v163
	ds_bpermute_b32 v160, v60, v54
	ds_bpermute_b32 v161, v60, v132
	ds_bpermute_b32 v162, v60, v134
	ds_bpermute_b32 v163, v60, v136
	s_waitcnt lgkmcnt(0)
	v_add_f32_e32 v54, v54, v160
	v_add_f32_e32 v132, v132, v161
	v_add_f32_e32 v134, v134, v162
	v_add_f32_e32 v136, v136, v163
	v_fmamk_f32 v54, v54, 0x3a000000, v235
	v_fmamk_f32 v132, v132, 0x3a000000, v235
	v_fmamk_f32 v134, v134, 0x3a000000, v235
	v_fmamk_f32 v136, v136, 0x3a000000, v235
	v_cmp_gt_f32_e64 s[4:5], s8, v54
	v_mul_f32_e32 v160, 0x4b800000, v54
	v_cmp_gt_f32_e64 s[6:7], s8, v132
	v_mul_f32_e32 v161, 0x4b800000, v132
	v_cndmask_b32_e64 v54, v54, v160, s[4:5]
	v_cndmask_b32_e64 v132, v132, v161, s[6:7]
	v_rsq_f32_e32 v54, v54
	v_rsq_f32_e32 v132, v132
	v_mul_f32_e32 v160, 0x45800000, v54
	v_mul_f32_e32 v161, 0x45800000, v132
	v_cndmask_b32_e64 v54, v54, v160, s[4:5]
	v_cndmask_b32_e64 v132, v132, v161, s[6:7]
	v_cmp_gt_f32_e64 s[4:5], s8, v134
	v_mul_f32_e32 v160, 0x4b800000, v134
	v_cmp_gt_f32_e64 s[6:7], s8, v136
	v_mul_f32_e32 v161, 0x4b800000, v136
	v_cndmask_b32_e64 v134, v134, v160, s[4:5]
	v_cndmask_b32_e64 v136, v136, v161, s[6:7]
	v_rsq_f32_e32 v134, v134
	v_rsq_f32_e32 v136, v136
	v_mul_f32_e32 v160, 0x45800000, v134
	v_mul_f32_e32 v161, 0x45800000, v136
	v_cndmask_b32_e64 v134, v134, v160, s[4:5]
	v_cndmask_b32_e64 v136, v136, v161, s[6:7]
	s_waitcnt vmcnt(12)
	v_lshlrev_b32_e32 v164, 16, v64
	v_and_b32_e32 v165, 0xffff0000, v64
	v_lshlrev_b32_e32 v166, 16, v65
	v_and_b32_e32 v167, 0xffff0000, v65
	v_pk_mul_f32 v[164:165], v[54:55], v[164:165] op_sel_hi:[0,1]
	v_pk_mul_f32 v[166:167], v[54:55], v[166:167] op_sel_hi:[0,1]
	v_pk_mul_f32 v[164:165], v[4:5], v[164:165]
	v_pk_mul_f32 v[166:167], v[6:7], v[166:167]
	global_store_dwordx4 v[52:53], v[164:167], off offset:-4096
	v_lshlrev_b32_e32 v168, 16, v66
	v_and_b32_e32 v169, 0xffff0000, v66
	v_lshlrev_b32_e32 v170, 16, v67
	v_and_b32_e32 v171, 0xffff0000, v67
	v_pk_mul_f32 v[168:169], v[54:55], v[168:169] op_sel_hi:[0,1]
	v_pk_mul_f32 v[170:171], v[54:55], v[170:171] op_sel_hi:[0,1]
	v_pk_mul_f32 v[168:169], v[0:1], v[168:169]
	v_pk_mul_f32 v[170:171], v[2:3], v[170:171]
	global_store_dwordx4 v[52:53], v[168:171], off offset:-4080
	v_lshlrev_b32_e32 v164, 16, v68
	v_and_b32_e32 v165, 0xffff0000, v68
	v_lshlrev_b32_e32 v166, 16, v69
	v_and_b32_e32 v167, 0xffff0000, v69
	v_pk_mul_f32 v[164:165], v[54:55], v[164:165] op_sel_hi:[0,1]
	v_pk_mul_f32 v[166:167], v[54:55], v[166:167] op_sel_hi:[0,1]
	v_pk_mul_f32 v[164:165], v[12:13], v[164:165]
	v_pk_mul_f32 v[166:167], v[14:15], v[166:167]
	global_store_dwordx4 v[52:53], v[164:167], off offset:-2048
	v_lshlrev_b32_e32 v168, 16, v70
	v_and_b32_e32 v169, 0xffff0000, v70
	v_lshlrev_b32_e32 v170, 16, v71
	v_and_b32_e32 v171, 0xffff0000, v71
	v_pk_mul_f32 v[168:169], v[54:55], v[168:169] op_sel_hi:[0,1]
	v_pk_mul_f32 v[170:171], v[54:55], v[170:171] op_sel_hi:[0,1]
	v_pk_mul_f32 v[168:169], v[8:9], v[168:169]
	v_pk_mul_f32 v[170:171], v[10:11], v[170:171]
	global_store_dwordx4 v[52:53], v[168:171], off offset:-2032
	v_lshlrev_b32_e32 v164, 16, v72
	v_and_b32_e32 v165, 0xffff0000, v72
	v_lshlrev_b32_e32 v166, 16, v73
	v_and_b32_e32 v167, 0xffff0000, v73
	v_pk_mul_f32 v[164:165], v[54:55], v[164:165] op_sel_hi:[0,1]
	v_pk_mul_f32 v[166:167], v[54:55], v[166:167] op_sel_hi:[0,1]
	v_pk_mul_f32 v[164:165], v[20:21], v[164:165]
	v_pk_mul_f32 v[166:167], v[22:23], v[166:167]
	global_store_dwordx4 v[52:53], v[164:167], off
	v_lshlrev_b32_e32 v168, 16, v74
	v_and_b32_e32 v169, 0xffff0000, v74
	v_lshlrev_b32_e32 v170, 16, v75
	v_and_b32_e32 v171, 0xffff0000, v75
	v_pk_mul_f32 v[168:169], v[54:55], v[168:169] op_sel_hi:[0,1]
	v_pk_mul_f32 v[170:171], v[54:55], v[170:171] op_sel_hi:[0,1]
	v_pk_mul_f32 v[168:169], v[16:17], v[168:169]
	v_pk_mul_f32 v[170:171], v[18:19], v[170:171]
	global_store_dwordx4 v[52:53], v[168:171], off offset:16
	v_lshlrev_b32_e32 v164, 16, v76
	v_and_b32_e32 v165, 0xffff0000, v76
	v_lshlrev_b32_e32 v166, 16, v77
	v_and_b32_e32 v167, 0xffff0000, v77
	v_pk_mul_f32 v[164:165], v[54:55], v[164:165] op_sel_hi:[0,1]
	v_pk_mul_f32 v[166:167], v[54:55], v[166:167] op_sel_hi:[0,1]
	v_pk_mul_f32 v[164:165], v[28:29], v[164:165]
	v_pk_mul_f32 v[166:167], v[30:31], v[166:167]
	global_store_dwordx4 v[52:53], v[164:167], off offset:2048
	v_lshlrev_b32_e32 v168, 16, v78
	v_and_b32_e32 v169, 0xffff0000, v78
	v_lshlrev_b32_e32 v170, 16, v79
	v_and_b32_e32 v171, 0xffff0000, v79
	v_pk_mul_f32 v[168:169], v[54:55], v[168:169] op_sel_hi:[0,1]
	v_pk_mul_f32 v[170:171], v[54:55], v[170:171] op_sel_hi:[0,1]
	v_pk_mul_f32 v[168:169], v[24:25], v[168:169]
	v_pk_mul_f32 v[170:171], v[26:27], v[170:171]
	global_store_dwordx4 v[52:53], v[168:171], off offset:2064
	s_waitcnt vmcnt(16)
	v_lshlrev_b32_e32 v164, 16, v80
	v_and_b32_e32 v165, 0xffff0000, v80
	v_lshlrev_b32_e32 v166, 16, v81
	v_and_b32_e32 v167, 0xffff0000, v81
	v_pk_mul_f32 v[164:165], v[132:133], v[164:165] op_sel_hi:[0,1]
	v_pk_mul_f32 v[166:167], v[132:133], v[166:167] op_sel_hi:[0,1]
	v_pk_mul_f32 v[164:165], v[4:5], v[164:165]
	v_pk_mul_f32 v[166:167], v[6:7], v[166:167]
	global_store_dwordx4 v[152:153], v[164:167], off offset:-4096
	v_lshlrev_b32_e32 v168, 16, v82
	v_and_b32_e32 v169, 0xffff0000, v82
	v_lshlrev_b32_e32 v170, 16, v83
	v_and_b32_e32 v171, 0xffff0000, v83
	v_pk_mul_f32 v[168:169], v[132:133], v[168:169] op_sel_hi:[0,1]
	v_pk_mul_f32 v[170:171], v[132:133], v[170:171] op_sel_hi:[0,1]
	v_pk_mul_f32 v[168:169], v[0:1], v[168:169]
	v_pk_mul_f32 v[170:171], v[2:3], v[170:171]
	global_store_dwordx4 v[152:153], v[168:171], off offset:-4080
	v_lshlrev_b32_e32 v164, 16, v84
	v_and_b32_e32 v165, 0xffff0000, v84
	v_lshlrev_b32_e32 v166, 16, v85
	v_and_b32_e32 v167, 0xffff0000, v85
	v_pk_mul_f32 v[164:165], v[132:133], v[164:165] op_sel_hi:[0,1]
	v_pk_mul_f32 v[166:167], v[132:133], v[166:167] op_sel_hi:[0,1]
	v_pk_mul_f32 v[164:165], v[12:13], v[164:165]
	v_pk_mul_f32 v[166:167], v[14:15], v[166:167]
	global_store_dwordx4 v[152:153], v[164:167], off offset:-2048
	v_lshlrev_b32_e32 v168, 16, v86
	v_and_b32_e32 v169, 0xffff0000, v86
	v_lshlrev_b32_e32 v170, 16, v87
	v_and_b32_e32 v171, 0xffff0000, v87
	v_pk_mul_f32 v[168:169], v[132:133], v[168:169] op_sel_hi:[0,1]
	v_pk_mul_f32 v[170:171], v[132:133], v[170:171] op_sel_hi:[0,1]
	v_pk_mul_f32 v[168:169], v[8:9], v[168:169]
	v_pk_mul_f32 v[170:171], v[10:11], v[170:171]
	global_store_dwordx4 v[152:153], v[168:171], off offset:-2032
	v_lshlrev_b32_e32 v164, 16, v88
	v_and_b32_e32 v165, 0xffff0000, v88
	v_lshlrev_b32_e32 v166, 16, v89
	v_and_b32_e32 v167, 0xffff0000, v89
	v_pk_mul_f32 v[164:165], v[132:133], v[164:165] op_sel_hi:[0,1]
	v_pk_mul_f32 v[166:167], v[132:133], v[166:167] op_sel_hi:[0,1]
	v_pk_mul_f32 v[164:165], v[20:21], v[164:165]
	v_pk_mul_f32 v[166:167], v[22:23], v[166:167]
	global_store_dwordx4 v[152:153], v[164:167], off
	v_lshlrev_b32_e32 v168, 16, v90
	v_and_b32_e32 v169, 0xffff0000, v90
	v_lshlrev_b32_e32 v170, 16, v91
	v_and_b32_e32 v171, 0xffff0000, v91
	v_pk_mul_f32 v[168:169], v[132:133], v[168:169] op_sel_hi:[0,1]
	v_pk_mul_f32 v[170:171], v[132:133], v[170:171] op_sel_hi:[0,1]
	v_pk_mul_f32 v[168:169], v[16:17], v[168:169]
	v_pk_mul_f32 v[170:171], v[18:19], v[170:171]
	global_store_dwordx4 v[152:153], v[168:171], off offset:16
	v_lshlrev_b32_e32 v164, 16, v92
	v_and_b32_e32 v165, 0xffff0000, v92
	v_lshlrev_b32_e32 v166, 16, v93
	v_and_b32_e32 v167, 0xffff0000, v93
	v_pk_mul_f32 v[164:165], v[132:133], v[164:165] op_sel_hi:[0,1]
	v_pk_mul_f32 v[166:167], v[132:133], v[166:167] op_sel_hi:[0,1]
	v_pk_mul_f32 v[164:165], v[28:29], v[164:165]
	v_pk_mul_f32 v[166:167], v[30:31], v[166:167]
	global_store_dwordx4 v[152:153], v[164:167], off offset:2048
	v_lshlrev_b32_e32 v168, 16, v94
	v_and_b32_e32 v169, 0xffff0000, v94
	v_lshlrev_b32_e32 v170, 16, v95
	v_and_b32_e32 v171, 0xffff0000, v95
	v_pk_mul_f32 v[168:169], v[132:133], v[168:169] op_sel_hi:[0,1]
	v_pk_mul_f32 v[170:171], v[132:133], v[170:171] op_sel_hi:[0,1]
	v_pk_mul_f32 v[168:169], v[24:25], v[168:169]
	v_pk_mul_f32 v[170:171], v[26:27], v[170:171]
	global_store_dwordx4 v[152:153], v[168:171], off offset:2064
	s_waitcnt vmcnt(20)
	v_lshlrev_b32_e32 v164, 16, v96
	v_and_b32_e32 v165, 0xffff0000, v96
	v_lshlrev_b32_e32 v166, 16, v97
	v_and_b32_e32 v167, 0xffff0000, v97
	v_pk_mul_f32 v[164:165], v[134:135], v[164:165] op_sel_hi:[0,1]
	v_pk_mul_f32 v[166:167], v[134:135], v[166:167] op_sel_hi:[0,1]
	v_pk_mul_f32 v[164:165], v[4:5], v[164:165]
	v_pk_mul_f32 v[166:167], v[6:7], v[166:167]
	global_store_dwordx4 v[154:155], v[164:167], off offset:-4096
	v_lshlrev_b32_e32 v168, 16, v98
	v_and_b32_e32 v169, 0xffff0000, v98
	v_lshlrev_b32_e32 v170, 16, v99
	v_and_b32_e32 v171, 0xffff0000, v99
	v_pk_mul_f32 v[168:169], v[134:135], v[168:169] op_sel_hi:[0,1]
	v_pk_mul_f32 v[170:171], v[134:135], v[170:171] op_sel_hi:[0,1]
	v_pk_mul_f32 v[168:169], v[0:1], v[168:169]
	v_pk_mul_f32 v[170:171], v[2:3], v[170:171]
	global_store_dwordx4 v[154:155], v[168:171], off offset:-4080
	v_lshlrev_b32_e32 v164, 16, v100
	v_and_b32_e32 v165, 0xffff0000, v100
	v_lshlrev_b32_e32 v166, 16, v101
	v_and_b32_e32 v167, 0xffff0000, v101
	v_pk_mul_f32 v[164:165], v[134:135], v[164:165] op_sel_hi:[0,1]
	v_pk_mul_f32 v[166:167], v[134:135], v[166:167] op_sel_hi:[0,1]
	v_pk_mul_f32 v[164:165], v[12:13], v[164:165]
	v_pk_mul_f32 v[166:167], v[14:15], v[166:167]
	global_store_dwordx4 v[154:155], v[164:167], off offset:-2048
	v_lshlrev_b32_e32 v168, 16, v102
	v_and_b32_e32 v169, 0xffff0000, v102
	v_lshlrev_b32_e32 v170, 16, v103
	v_and_b32_e32 v171, 0xffff0000, v103
	v_pk_mul_f32 v[168:169], v[134:135], v[168:169] op_sel_hi:[0,1]
	v_pk_mul_f32 v[170:171], v[134:135], v[170:171] op_sel_hi:[0,1]
	v_pk_mul_f32 v[168:169], v[8:9], v[168:169]
	v_pk_mul_f32 v[170:171], v[10:11], v[170:171]
	global_store_dwordx4 v[154:155], v[168:171], off offset:-2032
	v_lshlrev_b32_e32 v164, 16, v104
	v_and_b32_e32 v165, 0xffff0000, v104
	v_lshlrev_b32_e32 v166, 16, v105
	v_and_b32_e32 v167, 0xffff0000, v105
	v_pk_mul_f32 v[164:165], v[134:135], v[164:165] op_sel_hi:[0,1]
	v_pk_mul_f32 v[166:167], v[134:135], v[166:167] op_sel_hi:[0,1]
	v_pk_mul_f32 v[164:165], v[20:21], v[164:165]
	v_pk_mul_f32 v[166:167], v[22:23], v[166:167]
	global_store_dwordx4 v[154:155], v[164:167], off
	v_lshlrev_b32_e32 v168, 16, v106
	v_and_b32_e32 v169, 0xffff0000, v106
	v_lshlrev_b32_e32 v170, 16, v107
	v_and_b32_e32 v171, 0xffff0000, v107
	v_pk_mul_f32 v[168:169], v[134:135], v[168:169] op_sel_hi:[0,1]
	v_pk_mul_f32 v[170:171], v[134:135], v[170:171] op_sel_hi:[0,1]
	v_pk_mul_f32 v[168:169], v[16:17], v[168:169]
	v_pk_mul_f32 v[170:171], v[18:19], v[170:171]
	global_store_dwordx4 v[154:155], v[168:171], off offset:16
	v_lshlrev_b32_e32 v164, 16, v108
	v_and_b32_e32 v165, 0xffff0000, v108
	v_lshlrev_b32_e32 v166, 16, v109
	v_and_b32_e32 v167, 0xffff0000, v109
	v_pk_mul_f32 v[164:165], v[134:135], v[164:165] op_sel_hi:[0,1]
	v_pk_mul_f32 v[166:167], v[134:135], v[166:167] op_sel_hi:[0,1]
	v_pk_mul_f32 v[164:165], v[28:29], v[164:165]
	v_pk_mul_f32 v[166:167], v[30:31], v[166:167]
	global_store_dwordx4 v[154:155], v[164:167], off offset:2048
	v_lshlrev_b32_e32 v168, 16, v110
	v_and_b32_e32 v169, 0xffff0000, v110
	v_lshlrev_b32_e32 v170, 16, v111
	v_and_b32_e32 v171, 0xffff0000, v111
	v_pk_mul_f32 v[168:169], v[134:135], v[168:169] op_sel_hi:[0,1]
	v_pk_mul_f32 v[170:171], v[134:135], v[170:171] op_sel_hi:[0,1]
	v_pk_mul_f32 v[168:169], v[24:25], v[168:169]
	v_pk_mul_f32 v[170:171], v[26:27], v[170:171]
	global_store_dwordx4 v[154:155], v[168:171], off offset:2064
	s_waitcnt vmcnt(24)
	v_lshlrev_b32_e32 v164, 16, v112
	v_and_b32_e32 v165, 0xffff0000, v112
	v_lshlrev_b32_e32 v166, 16, v113
	v_and_b32_e32 v167, 0xffff0000, v113
	v_pk_mul_f32 v[164:165], v[136:137], v[164:165] op_sel_hi:[0,1]
	v_pk_mul_f32 v[166:167], v[136:137], v[166:167] op_sel_hi:[0,1]
	v_pk_mul_f32 v[164:165], v[4:5], v[164:165]
	v_pk_mul_f32 v[166:167], v[6:7], v[166:167]
	global_store_dwordx4 v[156:157], v[164:167], off offset:-4096
	v_lshlrev_b32_e32 v168, 16, v114
	v_and_b32_e32 v169, 0xffff0000, v114
	v_lshlrev_b32_e32 v170, 16, v115
	v_and_b32_e32 v171, 0xffff0000, v115
	v_pk_mul_f32 v[168:169], v[136:137], v[168:169] op_sel_hi:[0,1]
	v_pk_mul_f32 v[170:171], v[136:137], v[170:171] op_sel_hi:[0,1]
	v_pk_mul_f32 v[168:169], v[0:1], v[168:169]
	v_pk_mul_f32 v[170:171], v[2:3], v[170:171]
	global_store_dwordx4 v[156:157], v[168:171], off offset:-4080
	v_lshlrev_b32_e32 v164, 16, v116
	v_and_b32_e32 v165, 0xffff0000, v116
	v_lshlrev_b32_e32 v166, 16, v117
	v_and_b32_e32 v167, 0xffff0000, v117
	v_pk_mul_f32 v[164:165], v[136:137], v[164:165] op_sel_hi:[0,1]
	v_pk_mul_f32 v[166:167], v[136:137], v[166:167] op_sel_hi:[0,1]
	v_pk_mul_f32 v[164:165], v[12:13], v[164:165]
	v_pk_mul_f32 v[166:167], v[14:15], v[166:167]
	global_store_dwordx4 v[156:157], v[164:167], off offset:-2048
	v_lshlrev_b32_e32 v168, 16, v118
	v_and_b32_e32 v169, 0xffff0000, v118
	v_lshlrev_b32_e32 v170, 16, v119
	v_and_b32_e32 v171, 0xffff0000, v119
	v_pk_mul_f32 v[168:169], v[136:137], v[168:169] op_sel_hi:[0,1]
	v_pk_mul_f32 v[170:171], v[136:137], v[170:171] op_sel_hi:[0,1]
	v_pk_mul_f32 v[168:169], v[8:9], v[168:169]
	v_pk_mul_f32 v[170:171], v[10:11], v[170:171]
	global_store_dwordx4 v[156:157], v[168:171], off offset:-2032
	v_lshlrev_b32_e32 v164, 16, v120
	v_and_b32_e32 v165, 0xffff0000, v120
	v_lshlrev_b32_e32 v166, 16, v121
	v_and_b32_e32 v167, 0xffff0000, v121
	v_pk_mul_f32 v[164:165], v[136:137], v[164:165] op_sel_hi:[0,1]
	v_pk_mul_f32 v[166:167], v[136:137], v[166:167] op_sel_hi:[0,1]
	v_pk_mul_f32 v[164:165], v[20:21], v[164:165]
	v_pk_mul_f32 v[166:167], v[22:23], v[166:167]
	global_store_dwordx4 v[156:157], v[164:167], off
	v_lshlrev_b32_e32 v168, 16, v122
	v_and_b32_e32 v169, 0xffff0000, v122
	v_lshlrev_b32_e32 v170, 16, v123
	v_and_b32_e32 v171, 0xffff0000, v123
	v_pk_mul_f32 v[168:169], v[136:137], v[168:169] op_sel_hi:[0,1]
	v_pk_mul_f32 v[170:171], v[136:137], v[170:171] op_sel_hi:[0,1]
	v_pk_mul_f32 v[168:169], v[16:17], v[168:169]
	v_pk_mul_f32 v[170:171], v[18:19], v[170:171]
	global_store_dwordx4 v[156:157], v[168:171], off offset:16
	v_lshlrev_b32_e32 v164, 16, v124
	v_and_b32_e32 v165, 0xffff0000, v124
	v_lshlrev_b32_e32 v166, 16, v125
	v_and_b32_e32 v167, 0xffff0000, v125
	v_pk_mul_f32 v[164:165], v[136:137], v[164:165] op_sel_hi:[0,1]
	v_pk_mul_f32 v[166:167], v[136:137], v[166:167] op_sel_hi:[0,1]
	v_pk_mul_f32 v[164:165], v[28:29], v[164:165]
	v_pk_mul_f32 v[166:167], v[30:31], v[166:167]
	global_store_dwordx4 v[156:157], v[164:167], off offset:2048
	v_lshlrev_b32_e32 v168, 16, v126
	v_and_b32_e32 v169, 0xffff0000, v126
	v_lshlrev_b32_e32 v170, 16, v127
	v_and_b32_e32 v171, 0xffff0000, v127
	v_pk_mul_f32 v[168:169], v[136:137], v[168:169] op_sel_hi:[0,1]
	v_pk_mul_f32 v[170:171], v[136:137], v[170:171] op_sel_hi:[0,1]
	v_pk_mul_f32 v[168:169], v[24:25], v[168:169]
	v_pk_mul_f32 v[170:171], v[26:27], v[170:171]
	global_store_dwordx4 v[156:157], v[168:171], off offset:2064
	s_branch .LBB0_27
